# grid barrier rewritten by hand: static generation, XCD leader posts a non-returning add on the cross-XCD counter and every workgroup polls that counter (no TOPGEN/XGEN hops, no divisions)
# speedup vs baseline: 1.0100x; 1.0015x over previous
; __device__ __forceinline__ unsigned xb_ld(unsigned* p)              { return __hip_atomic_load(p, __ATOMIC_RELAXED, __HIP_MEMORY_SCOPE_AGENT); }
; __device__ __forceinline__ unsigned xb_add(unsigned* p, unsigned v) { return __hip_atomic_fetch_add(p, v, __ATOMIC_RELAXED, __HIP_MEMORY_SCOPE_AGENT); }
; #define XB_SPIN(cond, bar) do { unsigned _sp = 0; while (cond) { __builtin_amdgcn_s_sleep(1); \
;     if ((++_sp & 255u) == 0u) { if (xb_ld(&(bar)[XB_TMO])) break; if (_sp > XB_SPIN_CAP) { atomicAdd(&(bar)[XB_TMO], 1u); break; } } } } while (0)
; __device__ __forceinline__ void gemv_load(const float* W, int N, int n0, f32x4 (&wv)[16], int tid) {
;     const int cgp = tid & 7, kg = tid >> 3;
; #pragma unroll
;     for (int i = 0; i < 16; ++i) wv[i] = __builtin_nontemporal_load((const f32x4*)(W + (size_t)(kg + 64 * i) * N + n0 + 4 * cgp));
; }
; __device__ __forceinline__ void xcd_barrier(const XcdBarrier& b) {
;     asm volatile("s_waitcnt vmcnt(0)" ::: "memory");
;     __syncthreads();
;     if (threadIdx.x == 0) {
;         unsigned* bar = b.bar;
;         __builtin_amdgcn_s_waitcnt(0);
;         unsigned nloc = b.st[0], nx = b.st[1];
;         if (nloc == 0u) { xcd_barrier_complete(bar, b.x, nloc, nx); b.st[0] = nloc; b.st[1] = nx; }
;         const unsigned old = xb_add(&bar[XB_XSUB(b.x)], 1u);
;         const unsigned gen = old / nloc;
;         if (old + 1u == (gen + 1u) * nloc) {
;             __builtin_amdgcn_fence(__ATOMIC_RELEASE, "agent");
;             asm volatile("s_waitcnt vmcnt(0)" ::: "memory");
;             const unsigned og = xb_add(&bar[XB_TOP], 1u);
;             const unsigned tg = og / nx;
;             if (og + 1u == (tg + 1u) * nx) xb_add(&bar[XB_TOPGEN], 1u);
;             else XB_SPIN(xb_ld(&bar[XB_TOPGEN]) == tg, bar);
;             __builtin_amdgcn_fence(__ATOMIC_ACQUIRE, "agent");
;             xb_add(&bar[XB_XGEN(b.x)], 1u);
;             asm volatile("s_waitcnt vmcnt(0)" ::: "memory");
;         } else {
;             XB_SPIN(xb_ld(&bar[XB_XGEN(b.x)]) == gen, bar);
;             __builtin_amdgcn_fence(__ATOMIC_ACQUIRE, "agent");
;             asm volatile("s_waitcnt vmcnt(0)" ::: "memory");
;         }
;     }
;     __syncthreads();
; }
.LBB0_59:
	s_lshl_b32 s0, s33, 8
	v_readlane_b32 s4, v255, 1
	v_readlane_b32 s5, v255, 2
	s_add_u32 s10, s4, s0
	s_addc_u32 s11, s5, 0
	v_mov_b32_e32 v3, 0x1000
	v_mov_b32_e32 v4, 1
	global_atomic_add v3, v3, v4, s[10:11] offset:1024 sc0
	s_waitcnt lgkmcnt(0)
	v_readfirstlane_b32 s12, v2
	v_readfirstlane_b32 s13, v0
	s_mul_i32 s12, s12, 1
	s_mul_i32 s13, s13, 1
	v_mov_b32_e32 v1, 0xa3400
	s_mov_b32 s1, 0
	s_waitcnt vmcnt(0)
	buffer_inv sc1
	v_readfirstlane_b32 s0, v3
	s_add_i32 s0, s0, 1
	s_cmp_lg_u32 s0, s12
	s_cbranch_scc1 .Lgb1_poll
	buffer_wbl2 sc1
	s_waitcnt vmcnt(0)
	global_atomic_add v1, v4, s[24:25]
.Lgb1_poll:
	global_load_dword v5, v1, s[24:25] sc1
	s_add_i32 s1, s1, 1
	s_waitcnt vmcnt(0)
	v_readfirstlane_b32 s0, v5
	s_cmp_ge_u32 s0, s13
	s_cbranch_scc1 .Lgb1_done
	s_cmp_gt_u32 s1, 0x40000
	s_cbranch_scc1 .Lgb1_done
	s_sleep 1
	s_branch .Lgb1_poll
.Lgb1_done:
.LBB0_95:
	s_or_b64 exec, exec, s[6:7]
	s_waitcnt lgkmcnt(0)
	s_barrier
	s_load_dwordx2 s[34:35], s[96:97], 0
	s_load_dwordx2 s[4:5], s[96:97], 8
	s_load_dwordx2 s[6:7], s[96:97], 16
	s_load_dwordx2 s[8:9], s[96:97], 24
	s_load_dwordx2 s[38:39], s[96:97], 32
	s_load_dwordx2 s[40:41], s[96:97], 40
	s_load_dwordx2 s[36:37], s[96:97], 48
	s_load_dwordx2 s[10:11], s[96:97], 56
	s_load_dwordx2 s[12:13], s[96:97], 64
	s_load_dwordx2 s[14:15], s[96:97], 72
	s_load_dwordx2 s[42:43], s[96:97], 80
	s_load_dwordx2 s[16:17], s[96:97], 88
	s_load_dwordx2 s[44:45], s[96:97], 96
	s_load_dwordx2 s[18:19], s[96:97], 104
	s_load_dwordx2 s[46:47], s[96:97], 112
	s_load_dwordx2 s[20:21], s[96:97], 120
	s_load_dwordx2 s[30:31], s[96:97], 128
	s_waitcnt lgkmcnt(0)
	s_cmpk_gt_u32 s2, 0xaf
	s_cselect_b64 s[48:49], -1, 0
	s_and_b64 vcc, exec, s[48:49]
	v_lshrrev_b32_e32 v97, 9, v208
	s_cbranch_vccnz .LBB0_112
	s_lshl_b32 s8, s2, 5
	s_mov_b32 s9, 0
	s_lshl_b64 s[4:5], s[8:9], 2
	s_add_u32 s4, s44, s4
	v_and_b32_e32 v66, 28, v96
	s_addc_u32 s5, s45, s5
	v_mov_b32_e32 v69, 0
	v_lshlrev_b32_e32 v68, 2, v66
	v_mul_u32_u24_e32 v64, 0x1600, v174
	v_lshl_add_u64 v[0:1], s[4:5], 0, v[68:69]
	v_lshlrev_b32_e32 v68, 2, v64
	v_lshl_add_u64 v[56:57], v[0:1], 0, v[68:69]
	s_mov_b32 s0, 0x160000
	v_add_co_u32_e32 v8, vcc, s0, v56
	s_mov_b32 s0, 0x2c0000
	s_nop 0
	v_addc_co_u32_e32 v9, vcc, 0, v57, vcc
	v_add_co_u32_e32 v16, vcc, s0, v56
	s_mov_b32 s0, 0x420000
	s_nop 0
	v_addc_co_u32_e32 v17, vcc, 0, v57, vcc
	v_add_co_u32_e32 v18, vcc, s0, v56
	s_mov_b32 s0, 0x580000
	s_nop 0
	v_addc_co_u32_e32 v19, vcc, 0, v57, vcc
	v_add_co_u32_e32 v24, vcc, s0, v56
	s_mov_b32 s0, 0x6e0000
	s_nop 0
	v_addc_co_u32_e32 v25, vcc, 0, v57, vcc
	v_add_co_u32_e32 v26, vcc, s0, v56
	s_mov_b32 s0, 0x840000
	s_nop 0
	v_addc_co_u32_e32 v27, vcc, 0, v57, vcc
	v_add_co_u32_e32 v32, vcc, s0, v56
	s_mov_b32 s0, 0x9a0000
	s_nop 0
	v_addc_co_u32_e32 v33, vcc, 0, v57, vcc
	v_add_co_u32_e32 v34, vcc, s0, v56
	s_mov_b32 s0, 0xb00000
	s_nop 0
	v_addc_co_u32_e32 v35, vcc, 0, v57, vcc
	v_add_co_u32_e32 v40, vcc, s0, v56
	s_mov_b32 s0, 0xc60000
	s_nop 0
	v_addc_co_u32_e32 v41, vcc, 0, v57, vcc
	v_add_co_u32_e32 v42, vcc, s0, v56
	s_mov_b32 s0, 0xdc0000
	s_nop 0
	v_addc_co_u32_e32 v43, vcc, 0, v57, vcc
	v_add_co_u32_e32 v48, vcc, s0, v56
	s_mov_b32 s0, 0xf20000
	s_nop 0
	v_addc_co_u32_e32 v49, vcc, 0, v57, vcc
	v_add_co_u32_e32 v50, vcc, s0, v56
	s_mov_b32 s0, 0x1080000
	s_nop 0
	v_addc_co_u32_e32 v51, vcc, 0, v57, vcc
	v_add_co_u32_e32 v58, vcc, s0, v56
	s_mov_b32 s0, 0x11e0000
	s_nop 0
	v_addc_co_u32_e32 v59, vcc, 0, v57, vcc
	v_add_co_u32_e32 v60, vcc, s0, v56
	s_mov_b32 s0, 0x1340000
	s_nop 0
	v_addc_co_u32_e32 v61, vcc, 0, v57, vcc
	v_add_co_u32_e32 v70, vcc, s0, v56
	s_mov_b32 s0, 0x14a0000
	s_nop 0
	v_addc_co_u32_e32 v71, vcc, 0, v57, vcc
	v_add_co_u32_e32 v72, vcc, s0, v56
	global_load_dwordx4 v[0:3], v[56:57], off nt
	global_load_dwordx4 v[4:7], v[8:9], off nt
	s_nop 0
	global_load_dwordx4 v[8:11], v[16:17], off nt
	global_load_dwordx4 v[12:15], v[18:19], off nt
	s_nop 0
	global_load_dwordx4 v[16:19], v[24:25], off nt
	global_load_dwordx4 v[20:23], v[26:27], off nt
	s_nop 0
	global_load_dwordx4 v[24:27], v[32:33], off nt
	global_load_dwordx4 v[28:31], v[34:35], off nt
	s_nop 0
	global_load_dwordx4 v[32:35], v[40:41], off nt
	global_load_dwordx4 v[36:39], v[42:43], off nt
	s_nop 0
	global_load_dwordx4 v[40:43], v[48:49], off nt
	global_load_dwordx4 v[44:47], v[50:51], off nt
	s_nop 0
	global_load_dwordx4 v[48:51], v[58:59], off nt
	global_load_dwordx4 v[52:55], v[60:61], off nt
	v_addc_co_u32_e32 v73, vcc, 0, v57, vcc
	global_load_dwordx4 v[56:59], v[70:71], off nt
	global_load_dwordx4 v[60:63], v[72:73], off nt
	v_sub_u32_e32 v65, 14, v97
	v_lshrrev_b32_e32 v65, 1, v65
	v_add_u32_e32 v67, 1, v65
	v_add_u32_e32 v209, 0x200, v208
	v_and_b32_e32 v72, 12, v67
	v_add_u32_e32 v65, 0, v96
	s_mov_b64 s[6:7], 0
	v_mov_b64_e32 v[70:71], v[208:209]

; __device__ __forceinline__ unsigned xb_ld(unsigned* p)              { return __hip_atomic_load(p, __ATOMIC_RELAXED, __HIP_MEMORY_SCOPE_AGENT); }
; __device__ __forceinline__ unsigned xb_add(unsigned* p, unsigned v) { return __hip_atomic_fetch_add(p, v, __ATOMIC_RELAXED, __HIP_MEMORY_SCOPE_AGENT); }
; #define XB_SPIN(cond, bar) do { unsigned _sp = 0; while (cond) { __builtin_amdgcn_s_sleep(1); \
;     if ((++_sp & 255u) == 0u) { if (xb_ld(&(bar)[XB_TMO])) break; if (_sp > XB_SPIN_CAP) { atomicAdd(&(bar)[XB_TMO], 1u); break; } } } } while (0)
; __device__ __forceinline__ void xcd_barrier(const XcdBarrier& b) {
;     ...
;         const unsigned old = xb_add(&bar[XB_XSUB(b.x)], 1u);
;         const unsigned gen = old / nloc;
;         if (old + 1u == (gen + 1u) * nloc) {
;             __builtin_amdgcn_fence(__ATOMIC_RELEASE, "agent");
;             asm volatile("s_waitcnt vmcnt(0)" ::: "memory");
;             const unsigned og = xb_add(&bar[XB_TOP], 1u);
;             const unsigned tg = og / nx;
;             if (og + 1u == (tg + 1u) * nx) xb_add(&bar[XB_TOPGEN], 1u);
;             else XB_SPIN(xb_ld(&bar[XB_TOPGEN]) == tg, bar);
;             __builtin_amdgcn_fence(__ATOMIC_ACQUIRE, "agent");
;             xb_add(&bar[XB_XGEN(b.x)], 1u);
;             asm volatile("s_waitcnt vmcnt(0)" ::: "memory");
;         } else {
;             XB_SPIN(xb_ld(&bar[XB_XGEN(b.x)]) == gen, bar);
;             __builtin_amdgcn_fence(__ATOMIC_ACQUIRE, "agent");
;             asm volatile("s_waitcnt vmcnt(0)" ::: "memory");
;         }
.LBB0_217:
	s_lshl_b32 s0, s33, 8
	v_readlane_b32 s4, v255, 1
	v_readlane_b32 s5, v255, 2
	s_add_u32 s10, s4, s0
	s_addc_u32 s11, s5, 0
	v_mov_b32_e32 v3, 0x1000
	v_mov_b32_e32 v4, 1
	global_atomic_add v3, v3, v4, s[10:11] offset:1024 sc0
	s_waitcnt lgkmcnt(0)
	v_readfirstlane_b32 s12, v2
	v_readfirstlane_b32 s13, v0
	s_mul_i32 s12, s12, 2
	s_mul_i32 s13, s13, 2
	v_mov_b32_e32 v1, 0xa3400
	s_mov_b32 s1, 0
	s_waitcnt vmcnt(0)
	buffer_inv sc1
	v_readfirstlane_b32 s0, v3
	s_add_i32 s0, s0, 1
	s_cmp_lg_u32 s0, s12
	s_cbranch_scc1 .Lgb2_poll
	buffer_wbl2 sc1
	s_waitcnt vmcnt(0)
	global_atomic_add v1, v4, s[24:25]

; #define LAS __attribute__((address_space(3)))
; __device__ __forceinline__ unsigned xb_ld(unsigned* p)              { return __hip_atomic_load(p, __ATOMIC_RELAXED, __HIP_MEMORY_SCOPE_AGENT); }
; __device__ __forceinline__ unsigned xb_add(unsigned* p, unsigned v) { return __hip_atomic_fetch_add(p, v, __ATOMIC_RELAXED, __HIP_MEMORY_SCOPE_AGENT); }
; __device__ __forceinline__ void scan_item(const Params& p, LAS unsigned char* lds, int bh, int tid, int lane, int wave) {
;     const float* logf = (const float*)(p.ws + WS_LOGF); const int b = bh >> 3, h = bh & 7;
;     LAS float* wt = (LAS float*)lds;
;     float a[4];
; #pragma unroll
;     for (int i = 0; i < 4; ++i) a[i] = logf[((size_t)(b * S_ + 4 * tid + i)) * 8 + h];
;     a[1] += a[0]; a[2] += a[1]; a[3] += a[2];
;     float sc = a[3];
; #pragma unroll
;     for (int o = 1; o < 64; o <<= 1) { const float y = __shfl_up(sc, o); if (lane >= o) sc += y; }
;     if (lane == 63) wt[wave] = sc;
;     __syncthreads();
; __device__ __forceinline__ void xcd_barrier(const XcdBarrier& b) {
;     asm volatile("s_waitcnt vmcnt(0)" ::: "memory");
;     __syncthreads();
;     if (threadIdx.x == 0) {
;         unsigned* bar = b.bar;
;         __builtin_amdgcn_s_waitcnt(0);
;         unsigned nloc = b.st[0], nx = b.st[1];
;         if (nloc == 0u) { xcd_barrier_complete(bar, b.x, nloc, nx); b.st[0] = nloc; b.st[1] = nx; }
;         const unsigned old = xb_add(&bar[XB_XSUB(b.x)], 1u);
;         const unsigned gen = old / nloc;
;         if (old + 1u == (gen + 1u) * nloc) {
;             __builtin_amdgcn_fence(__ATOMIC_RELEASE, "agent");
;             asm volatile("s_waitcnt vmcnt(0)" ::: "memory");
;             const unsigned og = xb_add(&bar[XB_TOP], 1u);
;             const unsigned tg = og / nx;
;             if (og + 1u == (tg + 1u) * nx) xb_add(&bar[XB_TOPGEN], 1u);
;             else XB_SPIN(xb_ld(&bar[XB_TOPGEN]) == tg, bar);
;             __builtin_amdgcn_fence(__ATOMIC_ACQUIRE, "agent");
;             xb_add(&bar[XB_XGEN(b.x)], 1u);
;             asm volatile("s_waitcnt vmcnt(0)" ::: "memory");
;         } else {
;             XB_SPIN(xb_ld(&bar[XB_XGEN(b.x)]) == gen, bar);
;             __builtin_amdgcn_fence(__ATOMIC_ACQUIRE, "agent");
;             asm volatile("s_waitcnt vmcnt(0)" ::: "memory");
;         }
;     }
;     __syncthreads();
; }
.Lgb2_done:
.LBB0_253:
	s_or_b64 exec, exec, s[8:9]
	s_waitcnt lgkmcnt(0)
	s_barrier
	s_load_dwordx2 s[4:5], s[96:97], 0
	s_load_dwordx2 s[8:9], s[96:97], 8
	s_load_dwordx2 s[10:11], s[96:97], 16
	s_load_dwordx2 s[12:13], s[96:97], 24
	s_load_dwordx2 s[14:15], s[96:97], 32
	s_load_dwordx2 s[16:17], s[96:97], 40
	s_load_dwordx2 s[18:19], s[96:97], 48
	s_load_dwordx2 s[30:31], s[96:97], 56
	s_load_dwordx2 s[34:35], s[96:97], 64
	s_load_dwordx2 s[20:21], s[96:97], 72
	s_load_dwordx2 s[22:23], s[96:97], 80
	s_load_dwordx2 s[28:29], s[96:97], 88
	s_load_dwordx2 s[38:39], s[96:97], 96
	s_load_dwordx2 s[40:41], s[96:97], 104
	s_load_dwordx2 s[42:43], s[96:97], 112
	s_load_dwordx2 s[44:45], s[96:97], 120
	s_load_dwordx2 s[36:37], s[96:97], 128
	s_waitcnt lgkmcnt(0)
	s_cmp_gt_i32 s2, 63
	s_cbranch_scc1 .LBB0_265
	s_and_b32 s0, s2, 7
	s_lshl_b32 s1, s2, 8
	s_and_b32 s1, s1, 0xfffff800
	s_lshl_b32 s0, s0, 2
	v_add_u32_e32 v0, s1, v96
	s_add_u32 s0, s36, s0
	s_addc_u32 s1, s37, 0
	v_or_b32_e32 v4, 1, v0
	s_add_u32 s4, s0, 0x100000
	v_ashrrev_i32_e32 v5, 31, v4
	s_addc_u32 s5, s1, 0
	v_ashrrev_i32_e32 v1, 31, v0
	v_lshlrev_b64 v[4:5], 5, v[4:5]
	v_lshlrev_b64 v[2:3], 5, v[0:1]
	v_lshl_add_u64 v[6:7], s[4:5], 0, v[4:5]
	v_or_b32_e32 v4, 2, v0
	v_or_b32_e32 v0, 3, v0
	v_ashrrev_i32_e32 v5, 31, v4
	v_ashrrev_i32_e32 v1, 31, v0
	v_lshl_add_u64 v[2:3], s[4:5], 0, v[2:3]
	v_lshlrev_b64 v[4:5], 5, v[4:5]
	v_lshlrev_b64 v[0:1], 5, v[0:1]
	v_lshl_add_u64 v[8:9], s[4:5], 0, v[4:5]
	v_lshl_add_u64 v[0:1], s[4:5], 0, v[0:1]
	global_load_dword v4, v[2:3], off
	global_load_dword v5, v[6:7], off
	global_load_dword v10, v[8:9], off
	global_load_dword v11, v[0:1], off
	v_mbcnt_hi_u32_b32 v3, -1, v209
	v_and_b32_e32 v6, 64, v3
	v_add_u32_e32 v0, -1, v3
	v_cmp_lt_i32_e32 vcc, v0, v6
	v_add_u32_e32 v8, -4, v3
	s_waitcnt vmcnt(2)
	v_add_f32_e32 v2, v4, v5
	v_cndmask_b32_e32 v0, v0, v3, vcc
	s_waitcnt vmcnt(1)
	v_add_f32_e32 v1, v10, v2
	v_lshlrev_b32_e32 v7, 2, v0
	s_waitcnt vmcnt(0)
	v_add_f32_e32 v0, v11, v1
	ds_bpermute_b32 v5, v7, v0
	v_add_u32_e32 v7, -2, v3
	v_cmp_lt_i32_e32 vcc, v7, v6
	s_waitcnt lgkmcnt(0)
	v_add_f32_e32 v5, v0, v5
	v_cndmask_b32_e32 v7, v7, v3, vcc
	v_cmp_eq_u32_e32 vcc, 0, v154
	v_lshlrev_b32_e32 v7, 2, v7
	s_nop 0
	v_cndmask_b32_e32 v5, v5, v0, vcc
	ds_bpermute_b32 v7, v7, v5
	v_cmp_lt_i32_e32 vcc, v8, v6
	s_waitcnt lgkmcnt(0)
	v_add_f32_e32 v7, v5, v7
	v_cndmask_b32_e32 v8, v8, v3, vcc
	v_cmp_gt_u32_e32 vcc, 2, v154
	v_lshlrev_b32_e32 v8, 2, v8
	s_nop 0
	v_cndmask_b32_e32 v5, v7, v5, vcc
	ds_bpermute_b32 v7, v8, v5
	v_add_u32_e32 v8, -8, v3
	v_cmp_lt_i32_e32 vcc, v8, v6
	s_waitcnt lgkmcnt(0)
	v_add_f32_e32 v7, v5, v7
	v_cndmask_b32_e32 v8, v8, v3, vcc
	v_cmp_gt_u32_e32 vcc, 4, v154
	v_lshlrev_b32_e32 v8, 2, v8
	s_nop 0
	v_cndmask_b32_e32 v5, v7, v5, vcc
	ds_bpermute_b32 v7, v8, v5
	v_add_u32_e32 v8, -16, v3
	v_cmp_lt_i32_e32 vcc, v8, v6
	s_waitcnt lgkmcnt(0)
	v_add_f32_e32 v7, v5, v7
	v_cndmask_b32_e32 v8, v8, v3, vcc
	v_cmp_gt_u32_e32 vcc, 8, v154
	v_lshlrev_b32_e32 v8, 2, v8
	s_nop 0
	v_cndmask_b32_e32 v5, v7, v5, vcc
	ds_bpermute_b32 v7, v8, v5
	v_subrev_u32_e32 v8, 32, v3
	v_cmp_lt_i32_e32 vcc, v8, v6
	s_nop 1
	v_cndmask_b32_e32 v3, v8, v3, vcc
	v_lshlrev_b32_e32 v6, 2, v3
	s_waitcnt lgkmcnt(0)
	v_add_f32_e32 v3, v5, v7
	v_cmp_gt_u32_e32 vcc, 16, v154
	s_nop 1
	v_cndmask_b32_e32 v3, v3, v5, vcc
	ds_bpermute_b32 v5, v6, v3
	v_cmp_eq_u32_e32 vcc, 63, v154
	s_waitcnt lgkmcnt(0)
	v_add_f32_e32 v5, v3, v5
	s_and_saveexec_b64 s[8:9], vcc
	s_lshl_b32 s0, s58, 2
	s_add_i32 s0, s0, 0
	v_mov_b32_e32 v6, s0
	ds_write_b32 v6, v5
	s_or_b64 exec, exec, s[8:9]
	v_cndmask_b32_e64 v3, v5, v3, s[6:7]
	s_cmp_lt_u32 s3, 64
	v_sub_f32_e32 v3, v3, v0
	s_waitcnt lgkmcnt(0)
	s_barrier
	s_cbranch_scc1 .LBB0_264
	s_add_i32 s0, s58, -1
	s_cmp_lt_u32 s0, 7
	s_cbranch_scc1 .LBB0_261
	s_and_b32 s4, s58, 0x3fffff8
	s_mov_b32 s5, 0
	s_mov_b32 s8, 0

; __device__ __forceinline__ unsigned xb_ld(unsigned* p)              { return __hip_atomic_load(p, __ATOMIC_RELAXED, __HIP_MEMORY_SCOPE_AGENT); }
; __device__ __forceinline__ unsigned xb_add(unsigned* p, unsigned v) { return __hip_atomic_fetch_add(p, v, __ATOMIC_RELAXED, __HIP_MEMORY_SCOPE_AGENT); }
; #define XB_SPIN(cond, bar) do { unsigned _sp = 0; while (cond) { __builtin_amdgcn_s_sleep(1); \
;     if ((++_sp & 255u) == 0u) { if (xb_ld(&(bar)[XB_TMO])) break; if (_sp > XB_SPIN_CAP) { atomicAdd(&(bar)[XB_TMO], 1u); break; } } } } while (0)
; __device__ __forceinline__ void xcd_barrier(const XcdBarrier& b) {
;     ...
;         const unsigned old = xb_add(&bar[XB_XSUB(b.x)], 1u);
;         const unsigned gen = old / nloc;
;         if (old + 1u == (gen + 1u) * nloc) {
;             __builtin_amdgcn_fence(__ATOMIC_RELEASE, "agent");
;             asm volatile("s_waitcnt vmcnt(0)" ::: "memory");
;             const unsigned og = xb_add(&bar[XB_TOP], 1u);
;             const unsigned tg = og / nx;
;             if (og + 1u == (tg + 1u) * nx) xb_add(&bar[XB_TOPGEN], 1u);
;             else XB_SPIN(xb_ld(&bar[XB_TOPGEN]) == tg, bar);
;             __builtin_amdgcn_fence(__ATOMIC_ACQUIRE, "agent");
;             xb_add(&bar[XB_XGEN(b.x)], 1u);
;             asm volatile("s_waitcnt vmcnt(0)" ::: "memory");
;         } else {
;             XB_SPIN(xb_ld(&bar[XB_XGEN(b.x)]) == gen, bar);
;             __builtin_amdgcn_fence(__ATOMIC_ACQUIRE, "agent");
;             asm volatile("s_waitcnt vmcnt(0)" ::: "memory");
;         }
.LBB0_309:
	s_lshl_b32 s0, s33, 8
	v_readlane_b32 s4, v255, 1
	v_readlane_b32 s5, v255, 2
	s_add_u32 s10, s4, s0
	s_addc_u32 s11, s5, 0
	v_mov_b32_e32 v3, 0x1000
	v_mov_b32_e32 v4, 1
	global_atomic_add v3, v3, v4, s[10:11] offset:1024 sc0
	s_waitcnt lgkmcnt(0)
	v_readfirstlane_b32 s12, v2
	v_readfirstlane_b32 s13, v0
	s_mul_i32 s12, s12, 3
	s_mul_i32 s13, s13, 3
	v_mov_b32_e32 v1, 0xa3400
	s_mov_b32 s1, 0
	s_waitcnt vmcnt(0)
	buffer_inv sc1
	v_readfirstlane_b32 s0, v3
	s_add_i32 s0, s0, 1
	s_cmp_lg_u32 s0, s12
	s_cbranch_scc1 .Lgb3_poll
	buffer_wbl2 sc1
	s_waitcnt vmcnt(0)
	global_atomic_add v1, v4, s[24:25]

; #define LAS __attribute__((address_space(3)))
; __device__ __forceinline__ unsigned xb_ld(unsigned* p)              { return __hip_atomic_load(p, __ATOMIC_RELAXED, __HIP_MEMORY_SCOPE_AGENT); }
; #define XB_SPIN(cond, bar) do { unsigned _sp = 0; while (cond) { __builtin_amdgcn_s_sleep(1); \
;     if ((++_sp & 255u) == 0u) { if (xb_ld(&(bar)[XB_TMO])) break; if (_sp > XB_SPIN_CAP) { atomicAdd(&(bar)[XB_TMO], 1u); break; } } } } while (0)
; __device__ __forceinline__ void phase3(const Params& p, LAS unsigned char* lds, int tid, int lane, int wave) {
;     float mq = 0.f, mk = 0.f;
;     for (int i = 0; i < 64; ++i) { mq = fmaxf(mq, fabsf(p.qg[i])); mk = fmaxf(mk, fabsf(p.kg[i])); }
; __device__ __forceinline__ void xcd_barrier(const XcdBarrier& b) {
;     ...
;             XB_SPIN(xb_ld(&bar[XB_XGEN(b.x)]) == gen, bar);
;             __builtin_amdgcn_fence(__ATOMIC_ACQUIRE, "agent");
;             asm volatile("s_waitcnt vmcnt(0)" ::: "memory");
;         }
;     }
;     __syncthreads();
; }
.Lgb3_done:
.LBB0_345:
	s_or_b64 exec, exec, s[8:9]
	s_waitcnt lgkmcnt(0)
	s_barrier
	s_load_dwordx2 s[4:5], s[96:97], 0
	s_load_dwordx2 s[16:17], s[96:97], 8
	s_load_dwordx2 s[18:19], s[96:97], 16
	s_load_dwordx2 s[20:21], s[96:97], 24
	s_load_dwordx2 s[22:23], s[96:97], 32
	s_load_dwordx2 s[28:29], s[96:97], 40
	s_load_dwordx2 s[30:31], s[96:97], 48
	s_load_dwordx2 s[8:9], s[96:97], 56
	s_load_dwordx2 s[10:11], s[96:97], 64
	s_load_dwordx2 s[12:13], s[96:97], 72
	s_load_dwordx2 s[34:35], s[96:97], 80
	s_load_dwordx2 s[36:37], s[96:97], 88
	s_load_dwordx2 s[38:39], s[96:97], 96
	s_load_dwordx2 s[40:41], s[96:97], 104
	s_load_dwordx2 s[42:43], s[96:97], 112
	s_load_dwordx2 s[44:45], s[96:97], 120
	s_load_dwordx2 s[14:15], s[96:97], 128
	s_waitcnt lgkmcnt(0)
	s_mov_b64 s[16:17], 0
	v_mov_b32_e32 v2, 0
	v_mov_b32_e32 v1, 0
	v_mov_b32_e32 v0, 0

; __device__ __forceinline__ unsigned xb_ld(unsigned* p)              { return __hip_atomic_load(p, __ATOMIC_RELAXED, __HIP_MEMORY_SCOPE_AGENT); }
; __device__ __forceinline__ unsigned xb_add(unsigned* p, unsigned v) { return __hip_atomic_fetch_add(p, v, __ATOMIC_RELAXED, __HIP_MEMORY_SCOPE_AGENT); }
; #define XB_SPIN(cond, bar) do { unsigned _sp = 0; while (cond) { __builtin_amdgcn_s_sleep(1); \
;     if ((++_sp & 255u) == 0u) { if (xb_ld(&(bar)[XB_TMO])) break; if (_sp > XB_SPIN_CAP) { atomicAdd(&(bar)[XB_TMO], 1u); break; } } } } while (0)
; __device__ __forceinline__ void xcd_barrier(const XcdBarrier& b) {
;     ...
;         const unsigned old = xb_add(&bar[XB_XSUB(b.x)], 1u);
;         const unsigned gen = old / nloc;
;         if (old + 1u == (gen + 1u) * nloc) {
;             __builtin_amdgcn_fence(__ATOMIC_RELEASE, "agent");
;             asm volatile("s_waitcnt vmcnt(0)" ::: "memory");
;             const unsigned og = xb_add(&bar[XB_TOP], 1u);
;             const unsigned tg = og / nx;
;             if (og + 1u == (tg + 1u) * nx) xb_add(&bar[XB_TOPGEN], 1u);
;             else XB_SPIN(xb_ld(&bar[XB_TOPGEN]) == tg, bar);
;             __builtin_amdgcn_fence(__ATOMIC_ACQUIRE, "agent");
;             xb_add(&bar[XB_XGEN(b.x)], 1u);
;             asm volatile("s_waitcnt vmcnt(0)" ::: "memory");
;         } else {
;             XB_SPIN(xb_ld(&bar[XB_XGEN(b.x)]) == gen, bar);
;             __builtin_amdgcn_fence(__ATOMIC_ACQUIRE, "agent");
;             asm volatile("s_waitcnt vmcnt(0)" ::: "memory");
;         }
.LBB0_403:
	s_lshl_b32 s0, s33, 8
	v_readlane_b32 s4, v255, 1
	v_readlane_b32 s5, v255, 2
	s_add_u32 s10, s4, s0
	s_addc_u32 s11, s5, 0
	v_mov_b32_e32 v3, 0x1000
	v_mov_b32_e32 v4, 1
	global_atomic_add v3, v3, v4, s[10:11] offset:1024 sc0
	s_waitcnt lgkmcnt(0)
	v_readfirstlane_b32 s12, v2
	v_readfirstlane_b32 s13, v0
	s_mul_i32 s12, s12, 4
	s_mul_i32 s13, s13, 4
	v_mov_b32_e32 v1, 0xa3400
	s_mov_b32 s1, 0
	s_waitcnt vmcnt(0)
	buffer_inv sc1
	v_readfirstlane_b32 s0, v3
	s_add_i32 s0, s0, 1
	s_cmp_lg_u32 s0, s12
	s_cbranch_scc1 .Lgb4_poll
	buffer_wbl2 sc1
	s_waitcnt vmcnt(0)
	global_atomic_add v1, v4, s[24:25]

;     __host__ __device__ bool next(int i, Unit& u) const {
;         const long L = (long)i * G + c; if (L >= nwg) return false;
;         int wgid = (int)L; { const int q = nwg / NXCD, r = nwg % NXCD, xcd = wgid % NXCD, off = wgid / NXCD; wgid = (xcd < r ? xcd * (q + 1) : r * (q + 1) + (xcd - r) * q) + off; }
;         const int nig = WGM * nN, gid = wgid / nig, fm = gid * WGM, gsz = (nM - fm) < WGM ? (nM - fm) : WGM;
;         u.pm = fm + ((wgid % nig) % gsz); u.pn = (wgid % nig) / gsz; return true;
; __global__ void __launch_bounds__(512, 2) hymba_mega(Params p_arg) {
;     ...
;     {
;         const Params p = load_params();
;         pg8::Gemm g{(const bf16_t*)(p.ws + WS_MIX), (const bf16_t*)(p.ws + WS_WOUT), T_, 1024, 1024}; pg8::StaticOrder S; S.init(T_, 1024, G, bx);
;         EpiOut E{p.x, (const float*)(p.ws + WS_MOD), p.n2g, (bf16_t*)(p.ws + WS_Q), (bf16_t*)(p.ws + WS_H), (float*)(p.ws + WS_ROWSS), (bf16_t*)(p.ws + WS_TAIL)};
;         pg8::gemm_phase<EpiOut, pg8::StaticOrder, true, true>(lds, g, S, E);
.Lgb4_done:
.LBB0_439:
	s_or_b64 exec, exec, s[6:7]
	s_waitcnt lgkmcnt(0)
	s_barrier
	s_load_dwordx2 s[30:31], s[96:97], 0
	s_load_dwordx2 s[4:5], s[96:97], 8
	s_load_dwordx2 s[6:7], s[96:97], 16
	s_load_dwordx2 s[8:9], s[96:97], 24
	s_load_dwordx2 s[10:11], s[96:97], 32
	s_load_dwordx2 s[12:13], s[96:97], 40
	s_load_dwordx2 s[14:15], s[96:97], 48
	s_load_dwordx2 s[16:17], s[96:97], 56
	s_load_dwordx2 s[18:19], s[96:97], 64
	s_load_dwordx2 s[20:21], s[96:97], 72
	s_load_dwordx2 s[22:23], s[96:97], 80
	s_load_dwordx2 s[34:35], s[96:97], 88
	s_load_dwordx2 s[28:29], s[96:97], 96
	s_load_dwordx2 s[38:39], s[96:97], 104
	s_load_dwordx2 s[40:41], s[96:97], 112
	s_load_dwordx2 s[42:43], s[96:97], 120
	s_load_dwordx2 s[36:37], s[96:97], 128
	s_waitcnt lgkmcnt(0)
	v_mov_b32_e32 v9, v208
	s_cmpk_lt_i32 s2, 0x100
	v_and_b32_e32 v8, 0x1ff, v9
	s_cselect_b64 s[8:9], -1, 0
	s_cmpk_gt_i32 s2, 0xff
	v_readfirstlane_b32 s10, v8
	s_cbranch_scc1 .LBB0_445
	s_ashr_i32 s0, s2, 31
	s_lshr_b32 s0, s0, 29
	s_add_i32 s3, s2, s0
	s_and_b32 s0, s3, -8
	s_sub_i32 s4, s2, s0
	s_cmp_gt_i32 s4, -1
	s_cbranch_scc0 .LBB0_442
	s_lshl_b32 s5, s4, 5
	s_cbranch_execz .LBB0_443
	s_branch .LBB0_444

; __device__ __forceinline__ unsigned xb_ld(unsigned* p)              { return __hip_atomic_load(p, __ATOMIC_RELAXED, __HIP_MEMORY_SCOPE_AGENT); }
; __device__ __forceinline__ unsigned xb_add(unsigned* p, unsigned v) { return __hip_atomic_fetch_add(p, v, __ATOMIC_RELAXED, __HIP_MEMORY_SCOPE_AGENT); }
; #define XB_SPIN(cond, bar) do { unsigned _sp = 0; while (cond) { __builtin_amdgcn_s_sleep(1); \
;     if ((++_sp & 255u) == 0u) { if (xb_ld(&(bar)[XB_TMO])) break; if (_sp > XB_SPIN_CAP) { atomicAdd(&(bar)[XB_TMO], 1u); break; } } } } while (0)
; __device__ __forceinline__ void xcd_barrier(const XcdBarrier& b) {
;     ...
;         const unsigned old = xb_add(&bar[XB_XSUB(b.x)], 1u);
;         const unsigned gen = old / nloc;
;         if (old + 1u == (gen + 1u) * nloc) {
;             __builtin_amdgcn_fence(__ATOMIC_RELEASE, "agent");
;             asm volatile("s_waitcnt vmcnt(0)" ::: "memory");
;             const unsigned og = xb_add(&bar[XB_TOP], 1u);
;             const unsigned tg = og / nx;
;             if (og + 1u == (tg + 1u) * nx) xb_add(&bar[XB_TOPGEN], 1u);
;             else XB_SPIN(xb_ld(&bar[XB_TOPGEN]) == tg, bar);
;             __builtin_amdgcn_fence(__ATOMIC_ACQUIRE, "agent");
;             xb_add(&bar[XB_XGEN(b.x)], 1u);
;             asm volatile("s_waitcnt vmcnt(0)" ::: "memory");
;         } else {
;             XB_SPIN(xb_ld(&bar[XB_XGEN(b.x)]) == gen, bar);
;             __builtin_amdgcn_fence(__ATOMIC_ACQUIRE, "agent");
;             asm volatile("s_waitcnt vmcnt(0)" ::: "memory");
;         }
.LBB0_513:
	s_lshl_b32 s0, s33, 8
	v_readlane_b32 s4, v255, 1
	v_readlane_b32 s5, v255, 2
	s_add_u32 s10, s4, s0
	s_addc_u32 s11, s5, 0
	v_mov_b32_e32 v3, 0x1000
	v_mov_b32_e32 v4, 1
	global_atomic_add v3, v3, v4, s[10:11] offset:1024 sc0
	s_waitcnt lgkmcnt(0)
	v_readfirstlane_b32 s12, v2
	v_readfirstlane_b32 s13, v0
	s_mul_i32 s12, s12, 5
	s_mul_i32 s13, s13, 5
	v_mov_b32_e32 v1, 0xa3400
	s_mov_b32 s1, 0
	s_waitcnt vmcnt(0)
	buffer_inv sc1
	v_readfirstlane_b32 s0, v3
	s_add_i32 s0, s0, 1
	s_cmp_lg_u32 s0, s12
	s_cbranch_scc1 .Lgb5_poll
	buffer_wbl2 sc1
	s_waitcnt vmcnt(0)
	global_atomic_add v1, v4, s[24:25]

; #define LAS __attribute__((address_space(3)))
;     __host__ __device__ bool next(int i, Unit& u) const {
;         const long L = (long)i * G + c; if (L >= nwg) return false;
;         int wgid = (int)L; { const int q = nwg / NXCD, r = nwg % NXCD, xcd = wgid % NXCD, off = wgid / NXCD; wgid = (xcd < r ? xcd * (q + 1) : r * (q + 1) + (xcd - r) * q) + off; }
;         const int nig = WGM * nN, gid = wgid / nig, fm = gid * WGM, gsz = (nM - fm) < WGM ? (nM - fm) : WGM;
;         u.pm = fm + ((wgid % nig) % gsz); u.pn = (wgid % nig) / gsz; return true;
; __global__ void __launch_bounds__(512, 2) hymba_mega(Params p_arg) {
;     ...
;     {
;         const Params p = load_params();
;         pg8::Gemm g{(const bf16_t*)(p.ws + WS_H), (const bf16_t*)(p.ws + WS_WUP), 65 * 256, 2 * DFF, 1024};
;         UpOrder S; S.init(65 * 256, 2 * DFF, G, bx); S.tail_off = (long)WS_TAIL - (long)WS_H;
;         EpiUpF E{(const float*)(p.ws + WS_ROWSS), (const float*)(p.ws + WS_BIAS2), p.fcw, (bf16_t*)(p.ws + WS_ACT), (LAS float*)(lds + XCH_OFF)};
;         pg8::gemm_phase<EpiUpF, UpOrder, true, true>(lds, g, S, E);
.Lgb5_done:
.LBB0_549:
	s_or_b64 exec, exec, s[8:9]
	s_waitcnt lgkmcnt(0)
	s_barrier
	s_load_dwordx2 s[4:5], s[96:97], 0
	s_load_dwordx2 s[6:7], s[96:97], 8
	s_load_dwordx2 s[10:11], s[96:97], 16
	s_load_dwordx2 s[12:13], s[96:97], 24
	s_load_dwordx2 s[14:15], s[96:97], 32
	s_load_dwordx2 s[16:17], s[96:97], 40
	s_load_dwordx2 s[18:19], s[96:97], 48
	s_load_dwordx2 s[20:21], s[96:97], 56
	s_load_dwordx2 s[22:23], s[96:97], 64
	s_load_dwordx2 s[28:29], s[96:97], 72
	s_load_dwordx2 s[34:35], s[96:97], 80
	s_load_dwordx2 s[36:37], s[96:97], 88
	s_load_dwordx2 s[38:39], s[96:97], 96
	s_load_dwordx2 s[30:31], s[96:97], 104
	s_load_dwordx2 s[40:41], s[96:97], 112
	s_load_dwordx2 s[42:43], s[96:97], 120
	s_load_dwordx2 s[8:9], s[96:97], 128
	s_waitcnt lgkmcnt(0)
	v_mov_b32_e32 v9, v208
	s_cmpk_lt_i32 s2, 0x596
	v_and_b32_e32 v8, 0x1ff, v9
	s_cselect_b64 s[10:11], -1, 0
	s_cmpk_gt_i32 s2, 0x595
	v_readfirstlane_b32 s4, v8
	s_cbranch_scc1 .LBB0_555
	s_ashr_i32 s0, s2, 31
	s_lshr_b32 s0, s0, 29
	s_add_i32 s3, s2, s0
	s_and_b32 s0, s3, -8
	s_sub_i32 s5, s2, s0
	s_cmp_gt_i32 s5, 5
	s_cbranch_scc0 .LBB0_552
	s_mul_i32 s0, s5, 0xb2
	s_add_i32 s6, s0, 6
	s_cbranch_execz .LBB0_553
	s_branch .LBB0_554

; __device__ __forceinline__ unsigned xb_ld(unsigned* p)              { return __hip_atomic_load(p, __ATOMIC_RELAXED, __HIP_MEMORY_SCOPE_AGENT); }
; __device__ __forceinline__ unsigned xb_add(unsigned* p, unsigned v) { return __hip_atomic_fetch_add(p, v, __ATOMIC_RELAXED, __HIP_MEMORY_SCOPE_AGENT); }
; #define XB_SPIN(cond, bar) do { unsigned _sp = 0; while (cond) { __builtin_amdgcn_s_sleep(1); \
;     if ((++_sp & 255u) == 0u) { if (xb_ld(&(bar)[XB_TMO])) break; if (_sp > XB_SPIN_CAP) { atomicAdd(&(bar)[XB_TMO], 1u); break; } } } } while (0)
; __device__ __forceinline__ void xcd_barrier(const XcdBarrier& b) {
;     ...
;         const unsigned old = xb_add(&bar[XB_XSUB(b.x)], 1u);
;         const unsigned gen = old / nloc;
;         if (old + 1u == (gen + 1u) * nloc) {
;             __builtin_amdgcn_fence(__ATOMIC_RELEASE, "agent");
;             asm volatile("s_waitcnt vmcnt(0)" ::: "memory");
;             const unsigned og = xb_add(&bar[XB_TOP], 1u);
;             const unsigned tg = og / nx;
;             if (og + 1u == (tg + 1u) * nx) xb_add(&bar[XB_TOPGEN], 1u);
;             else XB_SPIN(xb_ld(&bar[XB_TOPGEN]) == tg, bar);
;             __builtin_amdgcn_fence(__ATOMIC_ACQUIRE, "agent");
;             xb_add(&bar[XB_XGEN(b.x)], 1u);
;             asm volatile("s_waitcnt vmcnt(0)" ::: "memory");
;         } else {
;             XB_SPIN(xb_ld(&bar[XB_XGEN(b.x)]) == gen, bar);
;             __builtin_amdgcn_fence(__ATOMIC_ACQUIRE, "agent");
;             asm volatile("s_waitcnt vmcnt(0)" ::: "memory");
;         }
.LBB0_617:
	s_lshl_b32 s0, s33, 8
	v_readlane_b32 s4, v255, 1
	v_readlane_b32 s5, v255, 2
	s_add_u32 s10, s4, s0
	s_addc_u32 s11, s5, 0
	v_mov_b32_e32 v3, 0x1000
	v_mov_b32_e32 v4, 1
	global_atomic_add v3, v3, v4, s[10:11] offset:1024 sc0
	s_waitcnt lgkmcnt(0)
	v_readfirstlane_b32 s12, v2
	v_readfirstlane_b32 s13, v0
	s_mul_i32 s12, s12, 6
	s_mul_i32 s13, s13, 6
	v_mov_b32_e32 v1, 0xa3400
	s_mov_b32 s1, 0
	s_waitcnt vmcnt(0)
	buffer_inv sc1
	v_readfirstlane_b32 s0, v3
	s_add_i32 s0, s0, 1
	s_cmp_lg_u32 s0, s12
	s_cbranch_scc1 .Lgb6_poll
	buffer_wbl2 sc1
	s_waitcnt vmcnt(0)
	global_atomic_add v1, v4, s[24:25]

; #define GSYNC() xcd_barrier(xbar)
;     __host__ __device__ bool next(int i, Unit& u) const {
;         const long L = (long)i * G + c; if (L >= nwg) return false;
;         int wgid = (int)L; { const int q = nwg / NXCD, r = nwg % NXCD, xcd = wgid % NXCD, off = wgid / NXCD; wgid = (xcd < r ? xcd * (q + 1) : r * (q + 1) + (xcd - r) * q) + off; }
;         const int nig = WGM * nN, gid = wgid / nig, fm = gid * WGM, gsz = (nM - fm) < WGM ? (nM - fm) : WGM;
;         u.pm = fm + ((wgid % nig) % gsz); u.pn = (wgid % nig) / gsz; return true;
; __global__ void __launch_bounds__(512, 2) hymba_mega(Params p_arg) {
;     ...
;     {
;         const Params p = load_params();
;         pg8::Gemm g{(const bf16_t*)(p.ws + WS_ACT), (const bf16_t*)(p.ws + WS_WDOWN), T_, 1024, DFF}; pg8::StaticOrder S; S.init(T_, 1024, G, bx);
;     ...
;         { EpiDown E0{(const float*)(p.ws + WS_MOD), (const bf16_t*)(p.ws + WS_Q), (float*)(p.ws + WS_K)};
;           pg8::gemm_phase<EpiDown, pg8::StaticOrder, true, true>(lds, g, S, E0); GSYNC(); }
;     ...
;         EpiDown E{(const float*)(p.ws + WS_MOD), (const bf16_t*)(p.ws + WS_Q), p.out};
;         pg8::gemm_phase<EpiDown, pg8::StaticOrder, true, true>(lds, g, S, E);
.Lgb6_done:
.LBB0_653:
	s_or_b64 exec, exec, s[8:9]
	s_waitcnt lgkmcnt(0)
	s_barrier
	s_load_dwordx2 s[0:1], s[96:97], 0
	s_load_dwordx2 s[4:5], s[96:97], 8
	s_load_dwordx2 s[6:7], s[96:97], 16
	s_load_dwordx2 s[12:13], s[96:97], 24
	s_load_dwordx2 s[14:15], s[96:97], 32
	s_load_dwordx2 s[16:17], s[96:97], 40
	s_load_dwordx2 s[18:19], s[96:97], 48
	s_load_dwordx2 s[20:21], s[96:97], 56
	s_load_dwordx2 s[22:23], s[96:97], 64
	s_load_dwordx2 s[24:25], s[96:97], 72
	s_load_dwordx2 s[28:29], s[96:97], 80
	s_load_dwordx2 s[30:31], s[96:97], 88
	s_load_dwordx2 s[34:35], s[96:97], 96
	s_load_dwordx2 s[36:37], s[96:97], 104
	s_load_dwordx2 s[38:39], s[96:97], 112
	s_load_dwordx2 s[8:9], s[96:97], 120
	s_load_dwordx2 s[10:11], s[96:97], 128
	s_waitcnt lgkmcnt(0)
	s_and_b64 vcc, exec, s[80:81]
	v_and_b32_e32 v0, 0x1ff, v208
	s_nop 0
	v_readfirstlane_b32 s4, v0
	s_cbranch_vccnz .LBB0_681
	s_ashr_i32 s3, s2, 31
	s_lshr_b32 s0, s3, 29
	s_add_i32 s7, s2, s0
	s_and_b32 s0, s7, -8
	s_sub_i32 s5, s2, s0
	s_cmp_gt_i32 s5, -1
	s_cbranch_scc0 .LBB0_656
	s_lshl_b32 s6, s5, 5
	s_ashr_i32 s1, s7, 3
	s_cbranch_execz .LBB0_657
	s_branch .LBB0_658
